# v_full6 + DPP hops also in the two full-norm row loops; norm row loops: gain vector loaded once before the loop (no per-row reload and drain), layer-1 norm prefetches the next row
# baseline (speedup 1.0000x reference)
.LBB0_113:
	s_or_b64 exec, exec, s[0:1]
	v_mov_b32_e32 v2, v180
	v_mov_b32_e32 v1, v180
	s_mov_b32 s0, s95
	v_ashrrev_i32_e32 v1, 6, v1
	s_nop 0
	v_lshl_add_u32 v18, s0, 3, v1
	s_mov_b32 s0, 0x8500
	v_cmp_gt_i32_e32 vcc, s0, v18
	s_and_saveexec_b64 s[10:11], vcc
	s_cbranch_execz .LBB0_144
	v_lshlrev_b32_e32 v3, 2, v2
	v_and_b32_e32 v4, 0xfc, v3
	s_add_u32 s0, s78, 0x43a1400
	v_bfrev_b32_e32 v5, 0.5
	s_movk_i32 s2, 0x80
	v_mov_b32_e32 v23, 0
	v_lshlrev_b32_e32 v22, 2, v4
	v_lshlrev_b32_e32 v2, 7, v2
	s_addc_u32 s1, s79, 0
	v_bitop3_b32 v1, v3, 4, v5 bitop3:0x6c
	v_bitop3_b32 v21, v3, 8, v5 bitop3:0x6c
	v_bitop3_b32 v40, v3, 16, v5 bitop3:0x6c
	v_bitop3_b32 v41, v3, 32, v5 bitop3:0x6c
	v_bitop3_b32 v42, v3, 64, v5 bitop3:0x6c
	v_bitop3_b32 v43, v3, s2, v5 bitop3:0x6c
	v_and_b32_e32 v20, 12, v3
	v_lshl_add_u64 v[24:25], s[50:51], 0, v[22:23]
	v_and_b32_e32 v22, 0x1e00, v2
	s_movk_i32 s2, 0x3e00
	v_mov_b32_e32 v3, 0x2000
	v_lshl_add_u64 v[26:27], s[0:1], 0, v[22:23]
	v_bitop3_b32 v22, v2, s2, v3 bitop3:0xc8
	s_movk_i32 s2, 0x5e00
	v_mov_b32_e32 v3, 0x4000
	v_lshl_add_u64 v[28:29], s[0:1], 0, v[22:23]
	v_bitop3_b32 v22, v2, s2, v3 bitop3:0xc8
	s_movk_i32 s2, 0x7e00
	v_mov_b32_e32 v3, 0x6000
	v_lshl_add_u64 v[30:31], s[0:1], 0, v[22:23]
	v_bitop3_b32 v22, v2, s2, v3 bitop3:0xc8
	v_lshl_add_u64 v[32:33], s[0:1], 0, v[22:23]
	s_mov_b64 s[16:17], 0
	s_mov_b32 s8, 0x8000
	s_movk_i32 s9, 0x7fff
	s_mov_b32 s12, 0x83ff
	s_mov_b32 s13, 0x8410
	s_mov_b32 s14, 0x8400
	v_mov_b32_e32 v44, 0x358637bd
	s_mov_b32 s15, 0x800000
	s_mov_b32 s18, 0x84ff
	v_lshlrev_b32_e32 v34, 2, v4
	global_load_dwordx4 v[192:195], v[24:25], off
	global_load_dwordx4 v[196:199], v[24:25], off offset:1024
	global_load_dwordx4 v[200:203], v[24:25], off offset:2048
	global_load_dwordx4 v[204:207], v[24:25], off offset:3072
	s_waitcnt vmcnt(0)
	s_branch .LBB0_116

.LBB0_132:
	s_or_b64 exec, exec, s[0:1]
	s_nop 0
	v_mov_b32_e32 v46, v192
	v_mov_b32_e32 v47, v193
	v_mov_b32_e32 v48, v194
	v_mov_b32_e32 v49, v195
	s_waitcnt vmcnt(0)
	v_pk_mul_f32 v[36:37], v[14:15], v[14:15]
	v_pk_mul_f32 v[38:39], v[16:17], v[16:17]
	v_mov_b32_e32 v50, v36
	v_mov_b32_e32 v51, v39
	v_pk_mov_b32 v[36:37], v[36:37], v[38:39] op_sel:[1,0]
	v_pk_mul_f32 v[38:39], v[6:7], v[6:7]
	v_pk_add_f32 v[36:37], v[36:37], v[50:51]
	v_pk_mul_f32 v[50:51], v[8:9], v[8:9]
	v_mov_b32_e32 v52, v38
	v_mov_b32_e32 v53, v51
	v_pk_mov_b32 v[38:39], v[38:39], v[50:51] op_sel:[1,0]
	v_mul_f32_e32 v19, v2, v2
	v_pk_add_f32 v[38:39], v[38:39], v[52:53]
	v_mul_f32_e32 v35, v3, v3
	v_pk_add_f32 v[36:37], v[36:37], v[36:37] op_sel:[0,1] op_sel_hi:[1,0]
	v_pk_add_f32 v[38:39], v[38:39], v[38:39] op_sel:[0,1] op_sel_hi:[1,0]
	v_mov_b32_e32 v37, v19
	v_mov_b32_e32 v39, v35
	v_pk_add_f32 v[36:37], v[36:37], v[38:39]
	v_mul_f32_e32 v38, v11, v11
	v_mul_f32_e32 v50, v13, v13
	v_mul_f32_e32 v45, v4, v4
	v_mul_f32_e32 v52, v5, v5
	v_pk_fma_f32 v[38:39], v[10:11], v[10:11], v[38:39] op_sel_hi:[1,1,0]
	v_pk_fma_f32 v[50:51], v[12:13], v[12:13], v[50:51] op_sel_hi:[1,1,0]
	v_mov_b32_e32 v39, v45
	v_mov_b32_e32 v51, v52
	v_pk_add_f32 v[38:39], v[38:39], v[50:51]
	v_cmp_gt_i32_e64 s[0:1], s14, v18
	v_pk_add_f32 v[36:37], v[36:37], v[38:39]
	v_ashrrev_i32_e32 v38, 14, v18
	v_add_f32_e32 v19, v36, v37
	v_and_b32_e32 v37, 15, v18
	v_add_u32_e32 v36, 0xffff8000, v18
	v_lshrrev_b32_e32 v36, 4, v36
	v_bfe_u32 v39, v18, 4, 10
	s_nop 1
	v_add_f32_dpp v19, v19, v19 quad_perm:[1,0,3,2] row_mask:0xf bank_mask:0xf
	v_mul_i32_i24_e32 v38, 0x401, v38
	v_add_u32_e32 v36, 0x802, v36
	v_add3_u32 v38, v38, v39, 1
	v_cndmask_b32_e64 v36, 0, v36, s[0:1]
	s_nop 1
	v_add_f32_dpp v19, v19, v19 quad_perm:[2,3,0,1] row_mask:0xf bank_mask:0xf
	v_cmp_gt_i32_e64 s[4:5], s13, v18
	v_cmp_lt_i32_e64 s[2:3], s12, v18
	v_cndmask_b32_e32 v36, v36, v38, vcc
	s_nop 1
	v_add_f32_dpp v19, v19, v19 row_half_mirror row_mask:0xf bank_mask:0xf
	s_nop 1
	v_add_f32_dpp v19, v19, v19 row_mirror row_mask:0xf bank_mask:0xf
	s_nop 0
	ds_bpermute_b32 v35, v42, v19
	s_waitcnt lgkmcnt(0)
	v_add_f32_e32 v19, v19, v35
	ds_bpermute_b32 v35, v43, v19
	s_waitcnt lgkmcnt(0)
	v_add_f32_e32 v19, v19, v35
	v_fmamk_f32 v19, v19, 0x3a800000, v44
	v_mul_f32_e32 v35, 0x4b800000, v19
	v_cmp_gt_f32_e64 s[6:7], s15, v19
	s_nop 1
	v_cndmask_b32_e64 v19, v19, v35, s[6:7]
	v_rsq_f32_e32 v35, v19
	v_cndmask_b32_e64 v19, v22, v37, s[0:1]
	v_cndmask_b32_e32 v19, v19, v37, vcc
	v_mul_f32_e32 v22, 0x45800000, v35
	v_cndmask_b32_e64 v35, v35, v22, s[6:7]
	v_mul_f32_e32 v14, v14, v35
	v_mul_f32_e32 v15, v15, v35
	v_mul_f32_e32 v16, v16, v35
	v_mul_f32_e32 v17, v17, v35
	s_waitcnt vmcnt(0)
	v_mul_f32_e32 v14, v46, v14
	v_mul_f32_e32 v15, v47, v15
	v_mul_f32_e32 v22, v48, v16
	v_mul_f32_e32 v17, v49, v17
	v_cvt_pk_bf16_f32 v16, v14, v15
	v_lshlrev_b32_e32 v14, 1, v20
	v_cvt_pk_bf16_f32 v17, v22, v17
	s_and_saveexec_b64 s[0:1], s[4:5]
	s_cbranch_execz .LBB0_135
	v_ashrrev_i32_e32 v37, 31, v36
	v_lshlrev_b64 v[38:39], 15, v[36:37]
	v_lshl_add_u64 v[38:39], v[26:27], 0, v[38:39]
	v_lshlrev_b32_e32 v22, 5, v19
	v_lshl_add_u64 v[38:39], v[38:39], 0, v[22:23]
	v_mov_b32_e32 v15, v23
	v_lshl_add_u64 v[38:39], v[38:39], 0, v[14:15]
	global_store_dwordx2 v[38:39], v[16:17], off
	s_and_b64 exec, exec, s[2:3]
	s_cbranch_execz .LBB0_135
	v_add_co_u32_e32 v38, vcc, 0x2008000, v38
	s_nop 1
	v_addc_co_u32_e32 v39, vcc, 0, v39, vcc
	global_store_dwordx2 v[38:39], v[16:17], off
.LBB0_135:
	s_or_b64 exec, exec, s[0:1]
	s_nop 0
	v_mov_b32_e32 v46, v196
	v_mov_b32_e32 v47, v197
	v_mov_b32_e32 v48, v198
	v_mov_b32_e32 v49, v199
	v_mul_f32_e32 v6, v6, v35
	v_mul_f32_e32 v7, v7, v35
	v_mul_f32_e32 v8, v8, v35
	v_mul_f32_e32 v9, v9, v35
	s_nop 0
	v_mul_f32_e32 v6, v6, v46
	v_mul_f32_e32 v7, v7, v47
	v_mul_f32_e32 v8, v8, v48
	v_mul_f32_e32 v9, v9, v49
	v_cvt_pk_bf16_f32 v6, v6, v7
	v_cvt_pk_bf16_f32 v7, v8, v9
	s_and_saveexec_b64 s[0:1], s[4:5]
	s_cbranch_execz .LBB0_138
	v_ashrrev_i32_e32 v37, 31, v36
	v_lshlrev_b64 v[8:9], 15, v[36:37]
	v_lshl_add_u64 v[8:9], v[28:29], 0, v[8:9]
	v_lshlrev_b32_e32 v22, 5, v19
	v_lshl_add_u64 v[8:9], v[8:9], 0, v[22:23]
	v_mov_b32_e32 v15, v23
	v_lshl_add_u64 v[8:9], v[8:9], 0, v[14:15]
	global_store_dwordx2 v[8:9], v[6:7], off
	s_and_b64 exec, exec, s[2:3]
	s_cbranch_execz .LBB0_138
	v_add_co_u32_e32 v8, vcc, 0x2008000, v8
	s_nop 1
	v_addc_co_u32_e32 v9, vcc, 0, v9, vcc
	global_store_dwordx2 v[8:9], v[6:7], off
.LBB0_138:
	s_or_b64 exec, exec, s[0:1]
	s_nop 0
	v_mov_b32_e32 v6, v200
	v_mov_b32_e32 v7, v201
	v_mov_b32_e32 v8, v202
	v_mov_b32_e32 v9, v203
	v_mul_f32_e32 v10, v10, v35
	v_mul_f32_e32 v11, v11, v35
	v_mul_f32_e32 v12, v12, v35
	v_mul_f32_e32 v13, v13, v35
	s_nop 0
	v_mul_f32_e32 v6, v10, v6
	v_mul_f32_e32 v7, v11, v7
	v_mul_f32_e32 v8, v12, v8
	v_mul_f32_e32 v9, v13, v9
	v_cvt_pk_bf16_f32 v6, v6, v7
	v_cvt_pk_bf16_f32 v7, v8, v9
	s_and_saveexec_b64 s[0:1], s[4:5]
	s_cbranch_execz .LBB0_141
	v_ashrrev_i32_e32 v37, 31, v36
	v_lshlrev_b64 v[8:9], 15, v[36:37]
	v_lshl_add_u64 v[8:9], v[30:31], 0, v[8:9]
	v_lshlrev_b32_e32 v22, 5, v19
	v_lshl_add_u64 v[8:9], v[8:9], 0, v[22:23]
	v_mov_b32_e32 v15, v23
	v_lshl_add_u64 v[8:9], v[8:9], 0, v[14:15]
	global_store_dwordx2 v[8:9], v[6:7], off
	s_and_b64 exec, exec, s[2:3]
	s_cbranch_execz .LBB0_141
	v_add_co_u32_e32 v8, vcc, 0x2008000, v8
	s_nop 1
	v_addc_co_u32_e32 v9, vcc, 0, v9, vcc
	global_store_dwordx2 v[8:9], v[6:7], off
.LBB0_141:
	s_or_b64 exec, exec, s[0:1]
	s_nop 0
	v_mov_b32_e32 v6, v204
	v_mov_b32_e32 v7, v205
	v_mov_b32_e32 v8, v206
	v_mov_b32_e32 v9, v207
	v_mul_f32_e32 v2, v2, v35
	v_mul_f32_e32 v3, v3, v35
	v_mul_f32_e32 v4, v4, v35
	v_mul_f32_e32 v5, v5, v35
	s_nop 0
	v_mul_f32_e32 v2, v2, v6
	v_mul_f32_e32 v3, v3, v7
	v_mul_f32_e32 v4, v4, v8
	v_mul_f32_e32 v5, v5, v9
	v_cvt_pk_bf16_f32 v2, v2, v3
	v_cvt_pk_bf16_f32 v3, v4, v5
	s_and_saveexec_b64 s[0:1], s[4:5]
	s_cbranch_execz .LBB0_115
	v_ashrrev_i32_e32 v37, 31, v36
	v_lshlrev_b64 v[4:5], 15, v[36:37]
	v_lshl_add_u64 v[4:5], v[32:33], 0, v[4:5]
	v_lshlrev_b32_e32 v22, 5, v19
	v_lshl_add_u64 v[4:5], v[4:5], 0, v[22:23]
	v_mov_b32_e32 v15, v23
	v_lshl_add_u64 v[4:5], v[4:5], 0, v[14:15]
	global_store_dwordx2 v[4:5], v[2:3], off
	s_and_b64 exec, exec, s[2:3]
	s_cbranch_execz .LBB0_115
	v_add_co_u32_e32 v4, vcc, 0x2008000, v4
	s_nop 1
	v_addc_co_u32_e32 v5, vcc, 0, v5, vcc
	global_store_dwordx2 v[4:5], v[2:3], off
	s_branch .LBB0_115

.LBB0_211:
	s_mov_b32 s0, s2
	v_writelane_b32 v252, s0, 20
	s_cmp_gt_u32 s2, 1
	s_nop 0
	v_writelane_b32 v252, s1, 21
	s_cselect_b64 s[0:1], -1, 0
	v_writelane_b32 v252, s0, 22
	s_and_b64 vcc, exec, s[0:1]
	s_nop 0
	v_writelane_b32 v252, s1, 23
	s_mov_b64 s[0:1], -1
	s_cbranch_vccnz .LBB0_740
	v_readlane_b32 s0, v252, 20
	v_readlane_b32 s1, v252, 21
	s_cmp_lg_u32 s0, 1
	s_cselect_b64 s[0:1], -1, 0
	v_writelane_b32 v252, s0, 24
	s_and_b64 vcc, exec, s[0:1]
	s_nop 0
	v_writelane_b32 v252, s1, 25
	s_cbranch_vccnz .LBB0_285
	v_mov_b32_e32 v0, v180
	v_mov_b32_e32 v1, v180
	s_mov_b32 s0, s95
	v_ashrrev_i32_e32 v1, 6, v1
	s_nop 0
	v_lshl_add_u32 v40, s0, 3, v1
	s_mov_b32 s0, 0x8500
	v_cmp_gt_i32_e32 vcc, s0, v40
	s_and_saveexec_b64 s[6:7], vcc
	s_cbranch_execz .LBB0_232
	v_lshlrev_b32_e32 v1, 2, v0
	s_movk_i32 s0, 0x80
	v_and_b32_e32 v2, 0xfc, v1
	v_bitop3_b32 v84, v1, s0, v186 bitop3:0x6c
	v_readlane_b32 s0, v254, 19
	v_lshlrev_b32_e32 v112, 2, v2
	v_readlane_b32 s1, v254, 20
	v_lshlrev_b32_e32 v0, 7, v0
	v_lshl_add_u64 v[42:43], s[74:75], 0, v[112:113]
	v_bitop3_b32 v45, v1, 4, v186 bitop3:0x6c
	v_bitop3_b32 v80, v1, 8, v186 bitop3:0x6c
	v_bitop3_b32 v81, v1, 16, v186 bitop3:0x6c
	v_bitop3_b32 v82, v1, 32, v186 bitop3:0x6c
	v_bitop3_b32 v83, v1, 64, v186 bitop3:0x6c
	v_and_b32_e32 v44, 12, v1
	v_or_b32_e32 v1, 0x100, v2
	v_lshl_add_u64 v[46:47], s[0:1], 0, v[112:113]
	v_and_b32_e32 v112, 0x1e00, v0
	v_lshl_add_u64 v[48:49], s[42:43], 0, v[112:113]
	v_lshlrev_b32_e32 v112, 2, v1
	v_lshlrev_b32_e32 v0, 5, v1
	v_or_b32_e32 v3, 0x200, v2
	v_lshl_add_u64 v[50:51], s[0:1], 0, v[112:113]
	v_and_b32_e32 v112, 0x3e00, v0
	v_lshl_add_u64 v[52:53], s[42:43], 0, v[112:113]
	v_lshlrev_b32_e32 v112, 2, v3
	v_lshlrev_b32_e32 v0, 5, v3
	v_or_b32_e32 v4, 0x300, v2
	v_lshl_add_u64 v[54:55], s[0:1], 0, v[112:113]
	v_and_b32_e32 v112, 0x5e00, v0
	v_lshl_add_u64 v[56:57], s[42:43], 0, v[112:113]
	v_lshlrev_b32_e32 v112, 2, v4
	v_lshlrev_b32_e32 v0, 5, v4
	v_lshl_add_u64 v[58:59], s[0:1], 0, v[112:113]
	v_and_b32_e32 v112, 0x7e00, v0
	v_lshl_add_u64 v[60:61], s[42:43], 0, v[112:113]
	v_lshlrev_b32_e32 v112, 1, v2
	v_lshl_add_u64 v[62:63], s[26:27], 0, v[112:113]
	s_mov_b64 s[8:9], 0
	v_mov_b32_e32 v216, v40
	v_ashrrev_i32_e32 v217, 31, v40
	v_lshlrev_b64 v[216:217], 11, v[216:217]
	v_lshl_add_u64 v[218:219], v[62:63], 0, v[216:217]
	global_load_dwordx2 v[208:209], v[218:219], off
	global_load_dwordx2 v[210:211], v[218:219], off offset:512
	global_load_dwordx2 v[212:213], v[218:219], off offset:1024
	global_load_dwordx2 v[214:215], v[218:219], off offset:1536
	global_load_dwordx4 v[192:195], v[46:47], off
	global_load_dwordx4 v[196:199], v[50:51], off
	global_load_dwordx4 v[200:203], v[54:55], off
	global_load_dwordx4 v[204:207], v[58:59], off
	s_waitcnt vmcnt(0)
	s_branch .LBB0_216

.LBB0_216:
	v_ashrrev_i32_e32 v41, 31, v40
	v_lshlrev_b64 v[0:1], 11, v[40:41]
	v_lshl_add_u64 v[64:65], v[62:63], 0, v[0:1]
	s_waitcnt vmcnt(0)
	v_mov_b32_e32 v6, v208
	v_mov_b32_e32 v7, v209
	v_mov_b32_e32 v4, v210
	v_mov_b32_e32 v5, v211
	v_mov_b32_e32 v2, v212
	v_mov_b32_e32 v3, v213
	v_mov_b32_e32 v0, v214
	v_mov_b32_e32 v1, v215
	v_lshl_add_u32 v216, s92, 3, v40
	v_min_i32_e32 v216, 0x84ff, v216
	v_ashrrev_i32_e32 v217, 31, v216
	v_lshlrev_b64 v[216:217], 11, v[216:217]
	v_lshl_add_u64 v[218:219], v[62:63], 0, v[216:217]
	global_load_dwordx2 v[208:209], v[218:219], off
	global_load_dwordx2 v[210:211], v[218:219], off offset:512
	global_load_dwordx2 v[212:213], v[218:219], off offset:1024
	global_load_dwordx2 v[214:215], v[218:219], off offset:1536
	s_nop 0
	s_nop 0
	s_nop 0
	v_cmp_gt_i32_e32 vcc, s97, v40
	v_add_u32_e32 v112, 0xffff8000, v40
	s_and_saveexec_b64 s[0:1], vcc
	s_xor_b64 s[0:1], exec, s[0:1]
	v_add_u32_e32 v112, 0xffff8000, v40
	s_or_saveexec_b64 s[0:1], s[0:1]
	s_nop 0
	v_lshlrev_b32_e32 v72, 16, v6
	v_and_b32_e32 v73, 0xffff0000, v6
	v_lshlrev_b32_e32 v74, 16, v7
	v_and_b32_e32 v75, 0xffff0000, v7
	s_nop 0
	v_lshlrev_b32_e32 v70, 16, v4
	v_and_b32_e32 v71, 0xffff0000, v4
	v_lshlrev_b32_e32 v68, 16, v5
	v_and_b32_e32 v69, 0xffff0000, v5
	s_nop 0
	v_lshlrev_b32_e32 v38, 16, v2
	v_and_b32_e32 v39, 0xffff0000, v2
	v_lshlrev_b32_e32 v36, 16, v3
	v_and_b32_e32 v37, 0xffff0000, v3
	s_nop 0
	v_lshlrev_b32_e32 v34, 16, v0
	v_and_b32_e32 v35, 0xffff0000, v0
	v_lshlrev_b32_e32 v32, 16, v1
	v_and_b32_e32 v33, 0xffff0000, v1
	s_xor_b64 exec, exec, s[0:1]
	s_cbranch_execz .LBB0_220
	v_lshlrev_b64 v[0:1], 12, v[112:113]
	v_lshl_add_u64 v[66:67], v[42:43], 0, v[0:1]
	v_add_co_u32_e32 v0, vcc, 0x500000, v66
	global_load_dwordx4 v[76:79], v[66:67], off
	global_load_dwordx4 v[86:89], v[66:67], off offset:1024
	global_load_dwordx4 v[90:93], v[66:67], off offset:2048
	global_load_dwordx4 v[24:27], v[66:67], off offset:3072
	v_addc_co_u32_e32 v1, vcc, 0, v67, vcc
	global_load_dwordx4 v[28:31], v[0:1], off
	global_load_dwordx4 v[20:23], v[0:1], off offset:1024
	global_load_dwordx4 v[16:19], v[0:1], off offset:2048
	v_add_co_u32_e32 v94, vcc, 0xa00000, v66
	global_load_dwordx4 v[12:15], v[0:1], off offset:3072
	s_nop 0
	v_addc_co_u32_e32 v95, vcc, 0, v67, vcc
	global_load_dwordx4 v[8:11], v[94:95], off
	global_load_dwordx4 v[4:7], v[94:95], off offset:1024
	global_load_dwordx4 v[0:3], v[94:95], off offset:2048
	s_mov_b32 s2, 0x1400000
	v_add_co_u32_e32 v106, vcc, s2, v66
	s_mov_b32 s2, 0x1900000
	s_nop 0
	v_addc_co_u32_e32 v107, vcc, 0, v67, vcc
	v_add_co_u32_e32 v108, vcc, s2, v66
	global_load_dwordx4 v[94:97], v[94:95], off offset:3072
	s_nop 0
	v_addc_co_u32_e32 v109, vcc, 0, v67, vcc
	v_add_co_u32_e32 v110, vcc, 0xf00000, v66
	s_mov_b32 s2, 0x1e00000
	s_nop 0
	v_addc_co_u32_e32 v111, vcc, 0, v67, vcc
	global_load_dwordx4 v[98:101], v[110:111], off
	global_load_dwordx4 v[102:105], v[110:111], off offset:1024
	s_waitcnt vmcnt(13)
	v_pk_add_f32 v[114:115], v[74:75], v[78:79]
	v_pk_add_f32 v[116:117], v[72:73], v[76:77]
	global_load_dwordx4 v[72:75], v[110:111], off offset:2048
	global_load_dwordx4 v[76:79], v[110:111], off offset:3072
	s_waitcnt vmcnt(14)
	v_pk_add_f32 v[88:89], v[68:69], v[88:89]
	v_pk_add_f32 v[86:87], v[70:71], v[86:87]
	s_waitcnt vmcnt(13)
	v_pk_add_f32 v[92:93], v[36:37], v[92:93]
	v_pk_add_f32 v[90:91], v[38:39], v[90:91]
	global_load_dwordx4 v[36:39], v[106:107], off
	global_load_dwordx4 v[68:71], v[106:107], off offset:1024
	s_waitcnt vmcnt(14)
	v_pk_add_f32 v[118:119], v[32:33], v[26:27]
	v_pk_add_f32 v[120:121], v[34:35], v[24:25]
	s_waitcnt vmcnt(13)
	v_pk_add_f32 v[116:117], v[116:117], v[28:29]
	v_pk_add_f32 v[114:115], v[114:115], v[30:31]
	global_load_dwordx4 v[24:27], v[106:107], off offset:2048
	global_load_dwordx4 v[28:31], v[106:107], off offset:3072
	s_waitcnt vmcnt(14)
	v_pk_add_f32 v[20:21], v[86:87], v[20:21]
	v_pk_add_f32 v[22:23], v[88:89], v[22:23]
	s_waitcnt vmcnt(13)
	v_pk_add_f32 v[16:17], v[90:91], v[16:17]
	v_pk_add_f32 v[18:19], v[92:93], v[18:19]
	global_load_dwordx4 v[32:35], v[108:109], off
	global_load_dwordx4 v[86:89], v[108:109], off offset:1024
	global_load_dwordx4 v[90:93], v[108:109], off offset:2048
	s_nop 0
	global_load_dwordx4 v[106:109], v[108:109], off offset:3072
	v_add_co_u32_e32 v110, vcc, s2, v66
	s_waitcnt vmcnt(16)
	v_pk_add_f32 v[12:13], v[120:121], v[12:13]
	v_addc_co_u32_e32 v111, vcc, 0, v67, vcc
	v_pk_add_f32 v[14:15], v[118:119], v[14:15]
	s_waitcnt vmcnt(15)
	v_pk_add_f32 v[10:11], v[114:115], v[10:11]
	v_pk_add_f32 v[8:9], v[116:117], v[8:9]
	global_load_dwordx4 v[114:117], v[110:111], off
	global_load_dwordx4 v[118:121], v[110:111], off offset:1024
	s_waitcnt vmcnt(16)
	v_pk_add_f32 v[6:7], v[22:23], v[6:7]
	v_pk_add_f32 v[4:5], v[20:21], v[4:5]
	global_load_dwordx4 v[20:23], v[110:111], off offset:2048
	s_waitcnt vmcnt(16)
	v_pk_add_f32 v[0:1], v[16:17], v[0:1]
	s_mov_b32 s2, 0x2300000
	s_waitcnt vmcnt(15)
	v_pk_add_f32 v[12:13], v[12:13], v[94:95]
	s_waitcnt vmcnt(14)
	v_pk_add_f32 v[94:95], v[10:11], v[100:101]
	s_waitcnt vmcnt(13)
	v_pk_add_f32 v[100:101], v[4:5], v[102:103]
	v_add_co_u32_e32 v4, vcc, s2, v66
	s_mov_b32 s2, 0x2800000
	s_nop 0
	v_addc_co_u32_e32 v5, vcc, 0, v67, vcc
	v_pk_add_f32 v[2:3], v[18:19], v[2:3]
	v_pk_add_f32 v[14:15], v[14:15], v[96:97]
	v_pk_add_f32 v[96:97], v[8:9], v[98:99]
	v_pk_add_f32 v[98:99], v[6:7], v[104:105]
	s_waitcnt vmcnt(12)
	v_pk_add_f32 v[72:73], v[0:1], v[72:73]
	v_pk_add_f32 v[74:75], v[2:3], v[74:75]
	s_waitcnt vmcnt(11)
	v_pk_add_f32 v[78:79], v[14:15], v[78:79]
	v_pk_add_f32 v[76:77], v[12:13], v[76:77]
	global_load_dwordx4 v[0:3], v[110:111], off offset:3072
	s_waitcnt vmcnt(11)
	v_pk_add_f32 v[38:39], v[94:95], v[38:39]
	v_pk_add_f32 v[36:37], v[96:97], v[36:37]
	s_waitcnt vmcnt(10)
	v_pk_add_f32 v[70:71], v[98:99], v[70:71]
	v_pk_add_f32 v[68:69], v[100:101], v[68:69]
	global_load_dwordx4 v[16:19], v[4:5], off
	global_load_dwordx4 v[12:15], v[4:5], off offset:1024
	global_load_dwordx4 v[8:11], v[4:5], off offset:2048
	s_nop 0
	global_load_dwordx4 v[4:7], v[4:5], off offset:3072
	s_waitcnt vmcnt(13)
	v_pk_add_f32 v[24:25], v[72:73], v[24:25]
	v_pk_add_f32 v[26:27], v[74:75], v[26:27]
	s_waitcnt vmcnt(12)
	v_pk_add_f32 v[30:31], v[78:79], v[30:31]
	v_pk_add_f32 v[28:29], v[76:77], v[28:29]
	s_waitcnt vmcnt(11)
	v_pk_add_f32 v[34:35], v[38:39], v[34:35]
	s_waitcnt vmcnt(9)
	v_pk_add_f32 v[122:123], v[24:25], v[90:91]
	v_add_co_u32_e32 v24, vcc, s2, v66
	s_mov_b32 s2, 0x2d00000
	s_nop 0
	v_addc_co_u32_e32 v25, vcc, 0, v67, vcc
	v_add_co_u32_e32 v98, vcc, s2, v66
	v_pk_add_f32 v[32:33], v[36:37], v[32:33]
	v_pk_add_f32 v[36:37], v[70:71], v[88:89]
	v_pk_add_f32 v[38:39], v[68:69], v[86:87]
	v_addc_co_u32_e32 v99, vcc, 0, v67, vcc
	s_mov_b32 s2, 0x3200000
	v_pk_add_f32 v[110:111], v[26:27], v[92:93]
	s_waitcnt vmcnt(8)
	v_pk_add_f32 v[68:69], v[30:31], v[108:109]
	v_pk_add_f32 v[70:71], v[28:29], v[106:107]
	s_waitcnt vmcnt(7)
	v_pk_add_f32 v[72:73], v[34:35], v[116:117]
	v_pk_add_f32 v[74:75], v[32:33], v[114:115]
	s_waitcnt vmcnt(6)
	v_pk_add_f32 v[76:77], v[36:37], v[120:121]
	v_pk_add_f32 v[78:79], v[38:39], v[118:119]
	global_load_dwordx4 v[36:39], v[24:25], off
	global_load_dwordx4 v[32:35], v[24:25], off offset:1024
	global_load_dwordx4 v[28:31], v[24:25], off offset:2048
	s_nop 0
	global_load_dwordx4 v[24:27], v[24:25], off offset:3072
	v_add_co_u32_e32 v66, vcc, s2, v66
	global_load_dwordx4 v[86:89], v[98:99], off
	global_load_dwordx4 v[90:93], v[98:99], off offset:1024
	global_load_dwordx4 v[94:97], v[98:99], off offset:2048
	s_nop 0
	global_load_dwordx4 v[98:101], v[98:99], off offset:3072
	v_addc_co_u32_e32 v67, vcc, 0, v67, vcc
	global_load_dwordx4 v[102:105], v[66:67], off
	global_load_dwordx4 v[106:109], v[66:67], off offset:1024
	s_waitcnt vmcnt(15)
	v_pk_add_f32 v[110:111], v[110:111], v[22:23]
	v_pk_add_f32 v[118:119], v[122:123], v[20:21]
	global_load_dwordx4 v[20:23], v[66:67], off offset:2048
	global_load_dwordx4 v[114:117], v[66:67], off offset:3072
	s_waitcnt vmcnt(16)
	v_pk_add_f32 v[0:1], v[70:71], v[0:1]
	v_pk_add_f32 v[2:3], v[68:69], v[2:3]
	s_waitcnt vmcnt(15)
	v_pk_add_f32 v[18:19], v[72:73], v[18:19]
	v_pk_add_f32 v[16:17], v[74:75], v[16:17]
	s_waitcnt vmcnt(14)
	v_pk_add_f32 v[14:15], v[76:77], v[14:15]
	s_waitcnt vmcnt(12)
	v_pk_add_f32 v[0:1], v[0:1], v[4:5]
	v_pk_add_f32 v[12:13], v[78:79], v[12:13]
	v_pk_add_f32 v[2:3], v[2:3], v[6:7]
	v_pk_add_f32 v[10:11], v[110:111], v[10:11]
	v_pk_add_f32 v[8:9], v[118:119], v[8:9]
	s_waitcnt vmcnt(11)
	v_pk_add_f32 v[4:5], v[18:19], v[38:39]
	v_pk_add_f32 v[6:7], v[16:17], v[36:37]
	s_waitcnt vmcnt(10)
	v_pk_add_f32 v[14:15], v[14:15], v[34:35]
	s_waitcnt vmcnt(8)
	v_pk_add_f32 v[0:1], v[0:1], v[24:25]
	v_pk_add_f32 v[12:13], v[12:13], v[32:33]
	s_waitcnt vmcnt(7)
	v_pk_add_f32 v[4:5], v[4:5], v[88:89]
	v_pk_add_f32 v[6:7], v[6:7], v[86:87]
	s_waitcnt vmcnt(4)
	v_pk_add_f32 v[0:1], v[0:1], v[98:99]
	v_pk_add_f32 v[10:11], v[10:11], v[30:31]
	v_pk_add_f32 v[8:9], v[8:9], v[28:29]
	v_pk_add_f32 v[2:3], v[2:3], v[26:27]
	v_pk_add_f32 v[14:15], v[14:15], v[92:93]
	v_pk_add_f32 v[12:13], v[12:13], v[90:91]
	s_waitcnt vmcnt(3)
	v_pk_add_f32 v[4:5], v[4:5], v[104:105]
	v_pk_add_f32 v[6:7], v[6:7], v[102:103]
	s_waitcnt vmcnt(0)
	v_pk_add_f32 v[0:1], v[0:1], v[114:115]
	v_pk_add_f32 v[10:11], v[10:11], v[96:97]
	v_pk_add_f32 v[8:9], v[8:9], v[94:95]
	v_pk_add_f32 v[2:3], v[2:3], v[100:101]
	v_pk_add_f32 v[14:15], v[14:15], v[108:109]
	v_pk_add_f32 v[12:13], v[12:13], v[106:107]
	v_pk_add_f32 v[74:75], v[4:5], 0 op_sel_hi:[1,0]
	v_pk_add_f32 v[72:73], v[6:7], 0 op_sel_hi:[1,0]
	v_pk_add_f32 v[34:35], v[0:1], 0 op_sel_hi:[1,0]
	v_cvt_pk_bf16_f32 v0, v72, v73
	v_cvt_pk_bf16_f32 v1, v74, v75
	v_pk_add_f32 v[10:11], v[10:11], v[22:23]
	v_pk_add_f32 v[8:9], v[8:9], v[20:21]
	v_pk_add_f32 v[2:3], v[2:3], v[116:117]
	v_pk_add_f32 v[68:69], v[14:15], 0 op_sel_hi:[1,0]
	v_pk_add_f32 v[70:71], v[12:13], 0 op_sel_hi:[1,0]
	global_store_dwordx2 v[64:65], v[0:1], off
	v_cvt_pk_bf16_f32 v0, v70, v71
	v_cvt_pk_bf16_f32 v1, v68, v69
	v_pk_add_f32 v[36:37], v[10:11], 0 op_sel_hi:[1,0]
	v_pk_add_f32 v[38:39], v[8:9], 0 op_sel_hi:[1,0]
	v_pk_add_f32 v[32:33], v[2:3], 0 op_sel_hi:[1,0]
	global_store_dwordx2 v[64:65], v[0:1], off offset:512
	v_cvt_pk_bf16_f32 v0, v38, v39
	v_cvt_pk_bf16_f32 v1, v36, v37
	global_store_dwordx2 v[64:65], v[0:1], off offset:1024
	v_cvt_pk_bf16_f32 v0, v34, v35
	v_cvt_pk_bf16_f32 v1, v32, v33
	global_store_dwordx2 v[64:65], v[0:1], off offset:1536
.LBB0_220:
	s_or_b64 exec, exec, s[0:1]
	s_nop 0
	v_mov_b32_e32 v2, v192
	v_mov_b32_e32 v3, v193
	v_mov_b32_e32 v4, v194
	v_mov_b32_e32 v5, v195
	v_pk_mul_f32 v[0:1], v[68:69], v[68:69]
	v_pk_mul_f32 v[6:7], v[70:71], v[70:71]
	v_pk_mul_f32 v[8:9], v[74:75], v[74:75]
	v_pk_mul_f32 v[10:11], v[72:73], v[72:73]
	v_mul_f32_e32 v12, v38, v38
	v_pk_mov_b32 v[16:17], v[10:11], v[8:9] op_sel:[1,0]
	v_mov_b32_e32 v11, v9
	v_pk_mov_b32 v[8:9], v[6:7], v[0:1] op_sel:[1,0]
	v_mov_b32_e32 v7, v1
	v_mul_f32_e32 v14, v36, v36
	v_pk_add_f32 v[10:11], v[16:17], v[10:11]
	v_pk_add_f32 v[6:7], v[8:9], v[6:7]
	v_pk_fma_f32 v[0:1], v[38:39], v[38:39], v[12:13] op_sel_hi:[1,1,0]
	v_pk_fma_f32 v[12:13], v[36:37], v[36:37], v[14:15] op_sel_hi:[1,1,0]
	v_pk_add_f32 v[8:9], v[10:11], v[10:11] op_sel_hi:[0,1]
	v_pk_add_f32 v[6:7], v[6:7], v[6:7] op_sel_hi:[0,1]
	v_mul_f32_e32 v0, v34, v34
	v_mul_f32_e32 v12, v35, v35
	v_mul_f32_e32 v8, v32, v32
	v_mul_f32_e32 v6, v33, v33
	v_pk_add_f32 v[0:1], v[0:1], v[12:13]
	v_pk_add_f32 v[6:7], v[8:9], v[6:7]
	s_mov_b32 s0, 0x8410
	v_pk_add_f32 v[0:1], v[0:1], v[6:7]
	v_cmp_gt_i32_e64 s[4:5], s0, v40
	v_add_f32_e32 v0, v0, v1
	v_lshrrev_b32_e32 v7, 4, v112
	s_mov_b32 s0, 0x83ff
	v_add_u32_e32 v6, 0xffff7c00, v40
	v_and_b32_e32 v8, 15, v40
	s_nop 1
	v_add_f32_dpp v0, v0, v0 quad_perm:[1,0,3,2] row_mask:0xf bank_mask:0xf
	v_cmp_lt_i32_e64 s[2:3], s0, v40
	v_add_u32_e32 v7, 0x802, v7
	v_cmp_gt_i32_e32 vcc, s63, v40
	s_mov_b32 s0, 0x800000
	s_nop 1
	v_add_f32_dpp v0, v0, v0 quad_perm:[2,3,0,1] row_mask:0xf bank_mask:0xf
	v_cndmask_b32_e32 v7, 0, v7, vcc
	v_cndmask_b32_e32 v6, v6, v8, vcc
	v_ashrrev_i32_e32 v9, 14, v40
	v_bfe_u32 v10, v40, 4, 10
	s_nop 1
	v_add_f32_dpp v0, v0, v0 row_half_mirror row_mask:0xf bank_mask:0xf
	v_mul_i32_i24_e32 v9, 0x401, v9
	v_add3_u32 v9, v9, v10, 1
	s_nop 1
	v_add_f32_dpp v0, v0, v0 row_mirror row_mask:0xf bank_mask:0xf
	s_nop 0
	ds_bpermute_b32 v1, v83, v0
	s_waitcnt lgkmcnt(0)
	v_add_f32_e32 v0, v0, v1
	ds_bpermute_b32 v1, v84, v0
	s_waitcnt lgkmcnt(0)
	v_add_f32_e32 v0, v0, v1
	v_fmamk_f32 v0, v0, 0x3a800000, v181
	v_mul_f32_e32 v1, 0x4b800000, v0
	v_cmp_gt_f32_e32 vcc, s0, v0
	v_cmp_gt_i32_e64 s[0:1], s97, v40
	s_nop 0
	v_cndmask_b32_e32 v0, v0, v1, vcc
	v_rsq_f32_e32 v1, v0
	v_cndmask_b32_e64 v8, v6, v8, s[0:1]
	v_cndmask_b32_e64 v0, v7, v9, s[0:1]
	v_mul_f32_e32 v6, 0x45800000, v1
	v_cndmask_b32_e32 v9, v1, v6, vcc
	v_mul_f32_e32 v1, v72, v9
	v_mul_f32_e32 v6, v73, v9
	v_mul_f32_e32 v7, v74, v9
	v_mul_f32_e32 v10, v75, v9
	s_nop 0
	v_mul_f32_e32 v1, v2, v1
	v_mul_f32_e32 v2, v3, v6
	v_mul_f32_e32 v3, v4, v7
	v_mul_f32_e32 v5, v5, v10
	v_cvt_pk_bf16_f32 v4, v1, v2
	v_lshlrev_b32_e32 v2, 1, v44
	v_cvt_pk_bf16_f32 v5, v3, v5
	s_and_saveexec_b64 s[0:1], s[4:5]
	s_cbranch_execz .LBB0_223
	v_ashrrev_i32_e32 v1, 31, v0
	v_lshlrev_b64 v[6:7], 15, v[0:1]
	v_lshl_add_u64 v[6:7], v[48:49], 0, v[6:7]
	v_lshlrev_b32_e32 v112, 5, v8
	v_lshl_add_u64 v[6:7], v[6:7], 0, v[112:113]
	v_mov_b32_e32 v3, v113
	v_lshl_add_u64 v[6:7], v[6:7], 0, v[2:3]
	global_store_dwordx2 v[6:7], v[4:5], off
	s_and_b64 exec, exec, s[2:3]
	s_cbranch_execz .LBB0_223
	v_add_co_u32_e32 v6, vcc, 0x2008000, v6
	s_nop 1
	v_addc_co_u32_e32 v7, vcc, 0, v7, vcc
	global_store_dwordx2 v[6:7], v[4:5], off
.LBB0_223:
	s_or_b64 exec, exec, s[0:1]
	s_nop 0
	v_mov_b32_e32 v4, v196
	v_mov_b32_e32 v5, v197
	v_mov_b32_e32 v6, v198
	v_mov_b32_e32 v7, v199
	v_mul_f32_e32 v3, v71, v9
	v_mul_f32_e32 v10, v68, v9
	v_mul_f32_e32 v1, v70, v9
	v_mul_f32_e32 v11, v69, v9
	s_nop 0
	v_mul_f32_e32 v3, v3, v5
	v_mul_f32_e32 v5, v10, v6
	v_mul_f32_e32 v1, v1, v4
	v_mul_f32_e32 v6, v11, v7
	v_cvt_pk_bf16_f32 v4, v1, v3
	v_cvt_pk_bf16_f32 v5, v5, v6
	s_and_saveexec_b64 s[0:1], s[4:5]
	s_cbranch_execz .LBB0_226
	v_ashrrev_i32_e32 v1, 31, v0
	v_lshlrev_b64 v[6:7], 15, v[0:1]
	v_lshl_add_u64 v[6:7], v[52:53], 0, v[6:7]
	v_lshlrev_b32_e32 v112, 5, v8
	v_lshl_add_u64 v[6:7], v[6:7], 0, v[112:113]
	v_mov_b32_e32 v3, v113
	v_lshl_add_u64 v[6:7], v[6:7], 0, v[2:3]
	global_store_dwordx2 v[6:7], v[4:5], off
	s_and_b64 exec, exec, s[2:3]
	s_cbranch_execz .LBB0_226
	v_add_co_u32_e32 v6, vcc, 0x2008000, v6
	s_nop 1
	v_addc_co_u32_e32 v7, vcc, 0, v7, vcc
	global_store_dwordx2 v[6:7], v[4:5], off
.LBB0_226:
	s_or_b64 exec, exec, s[0:1]
	s_nop 0
	v_mov_b32_e32 v4, v200
	v_mov_b32_e32 v5, v201
	v_mov_b32_e32 v6, v202
	v_mov_b32_e32 v7, v203
	v_mul_f32_e32 v3, v39, v9
	v_mul_f32_e32 v10, v36, v9
	v_mul_f32_e32 v1, v38, v9
	v_mul_f32_e32 v11, v37, v9
	s_nop 0
	v_mul_f32_e32 v3, v3, v5
	v_mul_f32_e32 v5, v10, v6
	v_mul_f32_e32 v1, v1, v4
	v_mul_f32_e32 v6, v11, v7
	v_cvt_pk_bf16_f32 v4, v1, v3
	v_cvt_pk_bf16_f32 v5, v5, v6
	s_and_saveexec_b64 s[0:1], s[4:5]
	s_cbranch_execz .LBB0_229
	v_ashrrev_i32_e32 v1, 31, v0
	v_lshlrev_b64 v[6:7], 15, v[0:1]
	v_lshl_add_u64 v[6:7], v[56:57], 0, v[6:7]
	v_lshlrev_b32_e32 v112, 5, v8
	v_lshl_add_u64 v[6:7], v[6:7], 0, v[112:113]
	v_mov_b32_e32 v3, v113
	v_lshl_add_u64 v[6:7], v[6:7], 0, v[2:3]
	global_store_dwordx2 v[6:7], v[4:5], off
	s_and_b64 exec, exec, s[2:3]
	s_cbranch_execz .LBB0_229
	v_add_co_u32_e32 v6, vcc, 0x2008000, v6
	s_nop 1
	v_addc_co_u32_e32 v7, vcc, 0, v7, vcc
	global_store_dwordx2 v[6:7], v[4:5], off
.LBB0_229:
	s_or_b64 exec, exec, s[0:1]
	s_nop 0
	v_mov_b32_e32 v4, v204
	v_mov_b32_e32 v5, v205
	v_mov_b32_e32 v6, v206
	v_mov_b32_e32 v7, v207
	v_mul_f32_e32 v3, v35, v9
	v_mul_f32_e32 v10, v32, v9
	v_mul_f32_e32 v1, v34, v9
	v_mul_f32_e32 v9, v33, v9
	s_nop 0
	v_mul_f32_e32 v3, v3, v5
	v_mul_f32_e32 v5, v10, v6
	v_mul_f32_e32 v1, v1, v4
	v_mul_f32_e32 v6, v9, v7
	v_cvt_pk_bf16_f32 v4, v1, v3
	v_cvt_pk_bf16_f32 v5, v5, v6
	s_and_saveexec_b64 s[0:1], s[4:5]
	s_cbranch_execz .LBB0_215
	v_ashrrev_i32_e32 v1, 31, v0
	v_lshlrev_b64 v[0:1], 15, v[0:1]
	v_lshl_add_u64 v[0:1], v[60:61], 0, v[0:1]
	v_lshlrev_b32_e32 v112, 5, v8
	v_lshl_add_u64 v[0:1], v[0:1], 0, v[112:113]
	v_mov_b32_e32 v3, v113
	v_lshl_add_u64 v[0:1], v[0:1], 0, v[2:3]
	global_store_dwordx2 v[0:1], v[4:5], off
	s_and_b64 exec, exec, s[2:3]
	s_cbranch_execz .LBB0_215
	v_add_co_u32_e32 v0, vcc, 0x2008000, v0
	s_nop 1
	v_addc_co_u32_e32 v1, vcc, 0, v1, vcc
	global_store_dwordx2 v[0:1], v[4:5], off
	s_branch .LBB0_215
